# phase-order split by bit 1 of workgroup id (XCD pairs 2,3,6,7 run HGRN/S5 output passes first) instead of bit 0
# baseline (speedup 1.0000x reference)
.Lord_att:
	s_mov_b64 s[10:11], s[84:85]
	s_waitcnt lgkmcnt(0)
	v_mov_b32_e32 v0, v173
	s_barrier
	s_getreg_b32 s1, hwreg(HW_REG_HW_ID, 0, 7)
	s_and_b32 s1, s1, 63
	s_lshl_b32 s1, s1, 2
	v_mov_b32_e32 v1, s1
	ds_read_b32 v6, v1
	s_load_dwordx8 s[12:19], s[10:11], 0x90
	v_and_b32_e32 v1, 63, v0
	s_lshl_b32 s66, s70, 6
	v_or_b32_e32 v160, s66, v1
	v_lshlrev_b64 v[2:3], 2, v[160:161]
	s_waitcnt lgkmcnt(0)
	v_lshl_add_u64 v[4:5], s[12:13], 0, v[2:3]
	global_load_dword v7, v[4:5], off
	v_lshl_add_u64 v[4:5], s[14:15], 0, v[2:3]
	global_load_dword v8, v[4:5], off
	v_lshl_add_u64 v[4:5], s[16:17], 0, v[2:3]
	v_lshl_add_u64 v[2:3], s[18:19], 0, v[2:3]
	global_load_dword v4, v[4:5], off
	v_readfirstlane_b32 s1, v6
	global_load_dword v2, v[2:3], off
	s_load_dwordx2 s[12:13], s[10:11], 0xb0
	s_getreg_b32 s6, hwreg(HW_REG_HW_ID, 0, 7)
	s_and_b32 s6, s6, 63
	s_lshl_b32 s6, s6, 2
	s_lshl_b32 s1, s1, 6
	s_and_b32 s1, s1, 0x3fc0
	s_waitcnt vmcnt(2)
	v_mul_f32_e32 v3, v7, v8
	ds_bpermute_b32 v3, v176, v3
	s_waitcnt vmcnt(0)
	v_mul_f32_e32 v5, v4, v2
	ds_bpermute_b32 v5, v176, v5
	s_waitcnt lgkmcnt(0)
	v_fmac_f32_e32 v3, v7, v8
	v_mov_b32_e32 v7, s6
	v_readlane_b32 s6, v255, 12
	v_readlane_b32 s7, v255, 13
	v_fmac_f32_e32 v5, v4, v2
	ds_bpermute_b32 v2, v177, v3
	ds_bpermute_b32 v4, v177, v5
	s_and_b64 vcc, exec, s[6:7]
	s_waitcnt lgkmcnt(1)
	v_add_f32_e32 v2, v3, v2
	s_waitcnt lgkmcnt(0)
	v_add_f32_e32 v3, v5, v4
	ds_bpermute_b32 v4, v178, v2
	ds_bpermute_b32 v5, v178, v3
	s_waitcnt lgkmcnt(1)
	v_add_f32_e32 v2, v2, v4
	s_waitcnt lgkmcnt(0)
	v_add_f32_e32 v3, v3, v5
	ds_bpermute_b32 v4, v179, v2
	ds_bpermute_b32 v5, v179, v3
	s_waitcnt lgkmcnt(1)
	v_add_f32_e32 v2, v2, v4
	s_waitcnt lgkmcnt(0)
	v_add_f32_e32 v3, v3, v5
	ds_bpermute_b32 v4, v180, v2
	ds_bpermute_b32 v6, v180, v3
	s_waitcnt lgkmcnt(1)
	v_add_f32_e32 v5, v2, v4
	s_waitcnt lgkmcnt(0)
	v_add_f32_e32 v3, v3, v6
	ds_bpermute_b32 v6, v181, v5
	ds_bpermute_b32 v4, v181, v3
	ds_read_b32 v2, v7
	s_waitcnt lgkmcnt(0)
	v_add_u32_e32 v2, s1, v0
	s_nop 0
	v_readfirstlane_b32 s1, v2
	s_cbranch_vccnz .LBB0_423
	s_cmp_eq_u32 s100, 1
	s_cbranch_scc1 .Lord_go
	s_bitcmp1_b32 s2, 1
	s_cbranch_scc0 .Lord_go
	s_mov_b32 s100, 2
	s_branch .LBB0_423
